# P0 silu staging: the 18 dependent one-at-a-time loads per thread issued together before the arithmetic
# baseline (speedup 1.0000x reference)
.LBB0_22:
	global_load_dword v100, v[6:7], off
	global_load_dword v101, v[6:7], off offset:2048
	v_add_co_u32_e32 v6, vcc, 0x1000, v6
	s_nop 1
	v_addc_co_u32_e32 v7, vcc, 0, v7, vcc
	global_load_dword v102, v[6:7], off
	global_load_dword v103, v[6:7], off offset:2048
	v_add_co_u32_e32 v6, vcc, 0x1000, v6
	s_nop 1
	v_addc_co_u32_e32 v7, vcc, 0, v7, vcc
	global_load_dword v104, v[6:7], off
	global_load_dword v105, v[6:7], off offset:2048
	v_add_co_u32_e32 v6, vcc, 0x1000, v6
	s_nop 1
	v_addc_co_u32_e32 v7, vcc, 0, v7, vcc
	global_load_dword v106, v[6:7], off
	global_load_dword v107, v[6:7], off offset:2048
	v_add_co_u32_e32 v6, vcc, 0x1000, v6
	s_nop 1
	v_addc_co_u32_e32 v7, vcc, 0, v7, vcc
	global_load_dword v108, v[6:7], off
	global_load_dword v109, v[6:7], off offset:2048
	v_add_co_u32_e32 v6, vcc, 0x1000, v6
	s_nop 1
	v_addc_co_u32_e32 v7, vcc, 0, v7, vcc
	global_load_dword v110, v[6:7], off
	global_load_dword v111, v[6:7], off offset:2048
	v_add_co_u32_e32 v6, vcc, 0x1000, v6
	s_nop 1
	v_addc_co_u32_e32 v7, vcc, 0, v7, vcc
	global_load_dword v112, v[6:7], off
	global_load_dword v113, v[6:7], off offset:2048
	v_add_co_u32_e32 v6, vcc, 0x1000, v6
	s_nop 1
	v_addc_co_u32_e32 v7, vcc, 0, v7, vcc
	global_load_dword v114, v[6:7], off
	global_load_dword v115, v[6:7], off offset:2048
	v_lshlrev_b32_e32 v8, 2, v145
	global_load_dword v116, v8, s[70:71]
	global_load_dword v117, v8, s[70:71] offset:2048
	s_waitcnt vmcnt(17)
	v_mul_f32_e32 v9, 0xbfb8aa3b, v100
	v_exp_f32_e32 v9, v9
	s_nop 0
	v_add_f32_e32 v9, 1.0, v9
	v_div_scale_f32 v10, s[12:13], v9, v9, v100
	v_rcp_f32_e32 v11, v10
	v_div_scale_f32 v12, vcc, v100, v9, v100
	v_fma_f32 v13, -v10, v11, 1.0
	v_fmac_f32_e32 v11, v13, v11
	v_mul_f32_e32 v13, v12, v11
	v_fma_f32 v14, -v10, v13, v12
	v_fmac_f32_e32 v13, v14, v11
	v_fma_f32 v10, -v10, v13, v12
	v_div_fmas_f32 v10, v10, v11, v13
	v_div_fixup_f32 v0, v10, v9, v100
	ds_write_b32 v5, v0
	v_add_u32_e32 v5, 0x800, v5
	s_waitcnt vmcnt(16)
	v_mul_f32_e32 v9, 0xbfb8aa3b, v101
	v_exp_f32_e32 v9, v9
	s_nop 0
	v_add_f32_e32 v9, 1.0, v9
	v_div_scale_f32 v10, s[12:13], v9, v9, v101
	v_rcp_f32_e32 v11, v10
	v_div_scale_f32 v12, vcc, v101, v9, v101
	v_fma_f32 v13, -v10, v11, 1.0
	v_fmac_f32_e32 v11, v13, v11
	v_mul_f32_e32 v13, v12, v11
	v_fma_f32 v14, -v10, v13, v12
	v_fmac_f32_e32 v13, v14, v11
	v_fma_f32 v10, -v10, v13, v12
	v_div_fmas_f32 v10, v10, v11, v13
	v_div_fixup_f32 v0, v10, v9, v101
	ds_write_b32 v5, v0
	v_add_u32_e32 v5, 0x800, v5
	s_waitcnt vmcnt(15)
	v_mul_f32_e32 v9, 0xbfb8aa3b, v102
	v_exp_f32_e32 v9, v9
	s_nop 0
	v_add_f32_e32 v9, 1.0, v9
	v_div_scale_f32 v10, s[12:13], v9, v9, v102
	v_rcp_f32_e32 v11, v10
	v_div_scale_f32 v12, vcc, v102, v9, v102
	v_fma_f32 v13, -v10, v11, 1.0
	v_fmac_f32_e32 v11, v13, v11
	v_mul_f32_e32 v13, v12, v11
	v_fma_f32 v14, -v10, v13, v12
	v_fmac_f32_e32 v13, v14, v11
	v_fma_f32 v10, -v10, v13, v12
	v_div_fmas_f32 v10, v10, v11, v13
	v_div_fixup_f32 v0, v10, v9, v102
	ds_write_b32 v5, v0
	v_add_u32_e32 v5, 0x800, v5
	s_waitcnt vmcnt(14)
	v_mul_f32_e32 v9, 0xbfb8aa3b, v103
	v_exp_f32_e32 v9, v9
	s_nop 0
	v_add_f32_e32 v9, 1.0, v9
	v_div_scale_f32 v10, s[12:13], v9, v9, v103
	v_rcp_f32_e32 v11, v10
	v_div_scale_f32 v12, vcc, v103, v9, v103
	v_fma_f32 v13, -v10, v11, 1.0
	v_fmac_f32_e32 v11, v13, v11
	v_mul_f32_e32 v13, v12, v11
	v_fma_f32 v14, -v10, v13, v12
	v_fmac_f32_e32 v13, v14, v11
	v_fma_f32 v10, -v10, v13, v12
	v_div_fmas_f32 v10, v10, v11, v13
	v_div_fixup_f32 v0, v10, v9, v103
	ds_write_b32 v5, v0
	v_add_u32_e32 v5, 0x800, v5
	s_waitcnt vmcnt(13)
	v_mul_f32_e32 v9, 0xbfb8aa3b, v104
	v_exp_f32_e32 v9, v9
	s_nop 0
	v_add_f32_e32 v9, 1.0, v9
	v_div_scale_f32 v10, s[12:13], v9, v9, v104
	v_rcp_f32_e32 v11, v10
	v_div_scale_f32 v12, vcc, v104, v9, v104
	v_fma_f32 v13, -v10, v11, 1.0
	v_fmac_f32_e32 v11, v13, v11
	v_mul_f32_e32 v13, v12, v11
	v_fma_f32 v14, -v10, v13, v12
	v_fmac_f32_e32 v13, v14, v11
	v_fma_f32 v10, -v10, v13, v12
	v_div_fmas_f32 v10, v10, v11, v13
	v_div_fixup_f32 v0, v10, v9, v104
	ds_write_b32 v5, v0
	v_add_u32_e32 v5, 0x800, v5
	s_waitcnt vmcnt(12)
	v_mul_f32_e32 v9, 0xbfb8aa3b, v105
	v_exp_f32_e32 v9, v9
	s_nop 0
	v_add_f32_e32 v9, 1.0, v9
	v_div_scale_f32 v10, s[12:13], v9, v9, v105
	v_rcp_f32_e32 v11, v10
	v_div_scale_f32 v12, vcc, v105, v9, v105
	v_fma_f32 v13, -v10, v11, 1.0
	v_fmac_f32_e32 v11, v13, v11
	v_mul_f32_e32 v13, v12, v11
	v_fma_f32 v14, -v10, v13, v12
	v_fmac_f32_e32 v13, v14, v11
	v_fma_f32 v10, -v10, v13, v12
	v_div_fmas_f32 v10, v10, v11, v13
	v_div_fixup_f32 v0, v10, v9, v105
	ds_write_b32 v5, v0
	v_add_u32_e32 v5, 0x800, v5
	s_waitcnt vmcnt(11)
	v_mul_f32_e32 v9, 0xbfb8aa3b, v106
	v_exp_f32_e32 v9, v9
	s_nop 0
	v_add_f32_e32 v9, 1.0, v9
	v_div_scale_f32 v10, s[12:13], v9, v9, v106
	v_rcp_f32_e32 v11, v10
	v_div_scale_f32 v12, vcc, v106, v9, v106
	v_fma_f32 v13, -v10, v11, 1.0
	v_fmac_f32_e32 v11, v13, v11
	v_mul_f32_e32 v13, v12, v11
	v_fma_f32 v14, -v10, v13, v12
	v_fmac_f32_e32 v13, v14, v11
	v_fma_f32 v10, -v10, v13, v12
	v_div_fmas_f32 v10, v10, v11, v13
	v_div_fixup_f32 v0, v10, v9, v106
	ds_write_b32 v5, v0
	v_add_u32_e32 v5, 0x800, v5
	s_waitcnt vmcnt(10)
	v_mul_f32_e32 v9, 0xbfb8aa3b, v107
	v_exp_f32_e32 v9, v9
	s_nop 0
	v_add_f32_e32 v9, 1.0, v9
	v_div_scale_f32 v10, s[12:13], v9, v9, v107
	v_rcp_f32_e32 v11, v10
	v_div_scale_f32 v12, vcc, v107, v9, v107
	v_fma_f32 v13, -v10, v11, 1.0
	v_fmac_f32_e32 v11, v13, v11
	v_mul_f32_e32 v13, v12, v11
	v_fma_f32 v14, -v10, v13, v12
	v_fmac_f32_e32 v13, v14, v11
	v_fma_f32 v10, -v10, v13, v12
	v_div_fmas_f32 v10, v10, v11, v13
	v_div_fixup_f32 v0, v10, v9, v107
	ds_write_b32 v5, v0
	v_add_u32_e32 v5, 0x800, v5
	s_waitcnt vmcnt(9)
	v_mul_f32_e32 v9, 0xbfb8aa3b, v108
	v_exp_f32_e32 v9, v9
	s_nop 0
	v_add_f32_e32 v9, 1.0, v9
	v_div_scale_f32 v10, s[12:13], v9, v9, v108
	v_rcp_f32_e32 v11, v10
	v_div_scale_f32 v12, vcc, v108, v9, v108
	v_fma_f32 v13, -v10, v11, 1.0
	v_fmac_f32_e32 v11, v13, v11
	v_mul_f32_e32 v13, v12, v11
	v_fma_f32 v14, -v10, v13, v12
	v_fmac_f32_e32 v13, v14, v11
	v_fma_f32 v10, -v10, v13, v12
	v_div_fmas_f32 v10, v10, v11, v13
	v_div_fixup_f32 v0, v10, v9, v108
	ds_write_b32 v5, v0
	v_add_u32_e32 v5, 0x800, v5
	s_waitcnt vmcnt(8)
	v_mul_f32_e32 v9, 0xbfb8aa3b, v109
	v_exp_f32_e32 v9, v9
	s_nop 0
	v_add_f32_e32 v9, 1.0, v9
	v_div_scale_f32 v10, s[12:13], v9, v9, v109
	v_rcp_f32_e32 v11, v10
	v_div_scale_f32 v12, vcc, v109, v9, v109
	v_fma_f32 v13, -v10, v11, 1.0
	v_fmac_f32_e32 v11, v13, v11
	v_mul_f32_e32 v13, v12, v11
	v_fma_f32 v14, -v10, v13, v12
	v_fmac_f32_e32 v13, v14, v11
	v_fma_f32 v10, -v10, v13, v12
	v_div_fmas_f32 v10, v10, v11, v13
	v_div_fixup_f32 v0, v10, v9, v109
	ds_write_b32 v5, v0
	v_add_u32_e32 v5, 0x800, v5
	s_waitcnt vmcnt(7)
	v_mul_f32_e32 v9, 0xbfb8aa3b, v110
	v_exp_f32_e32 v9, v9
	s_nop 0
	v_add_f32_e32 v9, 1.0, v9
	v_div_scale_f32 v10, s[12:13], v9, v9, v110
	v_rcp_f32_e32 v11, v10
	v_div_scale_f32 v12, vcc, v110, v9, v110
	v_fma_f32 v13, -v10, v11, 1.0
	v_fmac_f32_e32 v11, v13, v11
	v_mul_f32_e32 v13, v12, v11
	v_fma_f32 v14, -v10, v13, v12
	v_fmac_f32_e32 v13, v14, v11
	v_fma_f32 v10, -v10, v13, v12
	v_div_fmas_f32 v10, v10, v11, v13
	v_div_fixup_f32 v0, v10, v9, v110
	ds_write_b32 v5, v0
	v_add_u32_e32 v5, 0x800, v5
	s_waitcnt vmcnt(6)
	v_mul_f32_e32 v9, 0xbfb8aa3b, v111
	v_exp_f32_e32 v9, v9
	s_nop 0
	v_add_f32_e32 v9, 1.0, v9
	v_div_scale_f32 v10, s[12:13], v9, v9, v111
	v_rcp_f32_e32 v11, v10
	v_div_scale_f32 v12, vcc, v111, v9, v111
	v_fma_f32 v13, -v10, v11, 1.0
	v_fmac_f32_e32 v11, v13, v11
	v_mul_f32_e32 v13, v12, v11
	v_fma_f32 v14, -v10, v13, v12
	v_fmac_f32_e32 v13, v14, v11
	v_fma_f32 v10, -v10, v13, v12
	v_div_fmas_f32 v10, v10, v11, v13
	v_div_fixup_f32 v0, v10, v9, v111
	ds_write_b32 v5, v0
	v_add_u32_e32 v5, 0x800, v5
	s_waitcnt vmcnt(5)
	v_mul_f32_e32 v9, 0xbfb8aa3b, v112
	v_exp_f32_e32 v9, v9
	s_nop 0
	v_add_f32_e32 v9, 1.0, v9
	v_div_scale_f32 v10, s[12:13], v9, v9, v112
	v_rcp_f32_e32 v11, v10
	v_div_scale_f32 v12, vcc, v112, v9, v112
	v_fma_f32 v13, -v10, v11, 1.0
	v_fmac_f32_e32 v11, v13, v11
	v_mul_f32_e32 v13, v12, v11
	v_fma_f32 v14, -v10, v13, v12
	v_fmac_f32_e32 v13, v14, v11
	v_fma_f32 v10, -v10, v13, v12
	v_div_fmas_f32 v10, v10, v11, v13
	v_div_fixup_f32 v0, v10, v9, v112
	ds_write_b32 v5, v0
	v_add_u32_e32 v5, 0x800, v5
	s_waitcnt vmcnt(4)
	v_mul_f32_e32 v9, 0xbfb8aa3b, v113
	v_exp_f32_e32 v9, v9
	s_nop 0
	v_add_f32_e32 v9, 1.0, v9
	v_div_scale_f32 v10, s[12:13], v9, v9, v113
	v_rcp_f32_e32 v11, v10
	v_div_scale_f32 v12, vcc, v113, v9, v113
	v_fma_f32 v13, -v10, v11, 1.0
	v_fmac_f32_e32 v11, v13, v11
	v_mul_f32_e32 v13, v12, v11
	v_fma_f32 v14, -v10, v13, v12
	v_fmac_f32_e32 v13, v14, v11
	v_fma_f32 v10, -v10, v13, v12
	v_div_fmas_f32 v10, v10, v11, v13
	v_div_fixup_f32 v0, v10, v9, v113
	ds_write_b32 v5, v0
	v_add_u32_e32 v5, 0x800, v5
	s_waitcnt vmcnt(3)
	v_mul_f32_e32 v9, 0xbfb8aa3b, v114
	v_exp_f32_e32 v9, v9
	s_nop 0
	v_add_f32_e32 v9, 1.0, v9
	v_div_scale_f32 v10, s[12:13], v9, v9, v114
	v_rcp_f32_e32 v11, v10
	v_div_scale_f32 v12, vcc, v114, v9, v114
	v_fma_f32 v13, -v10, v11, 1.0
	v_fmac_f32_e32 v11, v13, v11
	v_mul_f32_e32 v13, v12, v11
	v_fma_f32 v14, -v10, v13, v12
	v_fmac_f32_e32 v13, v14, v11
	v_fma_f32 v10, -v10, v13, v12
	v_div_fmas_f32 v10, v10, v11, v13
	v_div_fixup_f32 v0, v10, v9, v114
	ds_write_b32 v5, v0
	v_add_u32_e32 v5, 0x800, v5
	s_waitcnt vmcnt(2)
	v_mul_f32_e32 v9, 0xbfb8aa3b, v115
	v_exp_f32_e32 v9, v9
	s_nop 0
	v_add_f32_e32 v9, 1.0, v9
	v_div_scale_f32 v10, s[12:13], v9, v9, v115
	v_rcp_f32_e32 v11, v10
	v_div_scale_f32 v12, vcc, v115, v9, v115
	v_fma_f32 v13, -v10, v11, 1.0
	v_fmac_f32_e32 v11, v13, v11
	v_mul_f32_e32 v13, v12, v11
	v_fma_f32 v14, -v10, v13, v12
	v_fmac_f32_e32 v13, v14, v11
	v_fma_f32 v10, -v10, v13, v12
	v_div_fmas_f32 v10, v10, v11, v13
	v_div_fixup_f32 v0, v10, v9, v115
	ds_write_b32 v5, v0
	v_add_u32_e32 v5, 0x800, v5
	s_waitcnt vmcnt(1)
	v_mul_f32_e32 v9, 0xbfb8aa3b, v116
	v_exp_f32_e32 v9, v9
	s_nop 0
	v_add_f32_e32 v9, 1.0, v9
	v_div_scale_f32 v10, s[12:13], v9, v9, v116
	v_rcp_f32_e32 v11, v10
	v_div_scale_f32 v12, vcc, v116, v9, v116
	v_fma_f32 v13, -v10, v11, 1.0
	v_fmac_f32_e32 v11, v13, v11
	v_mul_f32_e32 v13, v12, v11
	v_fma_f32 v14, -v10, v13, v12
	v_fmac_f32_e32 v13, v14, v11
	v_fma_f32 v10, -v10, v13, v12
	v_div_fmas_f32 v10, v10, v11, v13
	v_div_fixup_f32 v0, v10, v9, v116
	ds_write_b32 v5, v0
	v_add_u32_e32 v5, 0x800, v5
	s_waitcnt vmcnt(0)
	v_mul_f32_e32 v9, 0xbfb8aa3b, v117
	v_exp_f32_e32 v9, v9
	s_nop 0
	v_add_f32_e32 v9, 1.0, v9
	v_div_scale_f32 v10, s[12:13], v9, v9, v117
	v_rcp_f32_e32 v11, v10
	v_div_scale_f32 v12, vcc, v117, v9, v117
	v_fma_f32 v13, -v10, v11, 1.0
	v_fmac_f32_e32 v11, v13, v11
	v_mul_f32_e32 v13, v12, v11
	v_fma_f32 v14, -v10, v13, v12
	v_fmac_f32_e32 v13, v14, v11
	v_fma_f32 v10, -v10, v13, v12
	v_div_fmas_f32 v10, v10, v11, v13
	v_div_fixup_f32 v0, v10, v9, v117
	ds_write_b32 v5, v0
	v_add_u32_e32 v5, 0x800, v5
	s_or_b64 exec, exec, s[10:11]
	v_ashrrev_i32_e32 v5, 31, v4
	v_mov_b32_e32 v8, 0
	v_lshl_add_u64 v[6:7], v[4:5], 2, s[6:7]
	v_lshlrev_b32_e32 v68, 2, v4
	s_mov_b64 s[10:11], 0
	s_mov_b32 s12, s16
	v_mov_b32_e32 v9, v8
	v_mov_b32_e32 v10, v8
	v_mov_b32_e32 v11, v8
	v_mov_b32_e32 v12, v8
	v_mov_b32_e32 v13, v8
	v_mov_b32_e32 v14, v8
	v_mov_b32_e32 v15, v8
	v_mov_b32_e32 v0, v8
	s_waitcnt lgkmcnt(0)
	s_barrier
